# 5us start stagger of odd workgroups in four store-heavy GEMM phases (timing-only)
# speedup vs baseline: 1.0015x; 1.0015x over previous
.LBB0_40:
	v_readlane_b32 s3, v254, 48
	s_bitcmp1_b32 s3, 0
	s_cbranch_scc0 .Lstag_P2_done
	s_memrealtime s[40:41]
	s_waitcnt lgkmcnt(0)
	s_add_u32 s43, s40, 500
.Lstag_P2_loop:
	s_sleep 16
	s_memrealtime s[40:41]
	s_waitcnt lgkmcnt(0)
	s_sub_u32 s41, s40, s43
	s_cmp_lt_i32 s41, 0
	s_cbranch_scc1 .Lstag_P2_loop

.LBB0_72:
	v_readlane_b32 s2, v250, 23
	v_mov_b32_e32 v3, v222
	v_readlane_b32 s3, v250, 24
	s_andn2_b64 vcc, exec, s[2:3]
	v_readfirstlane_b32 s16, v3
	s_cbranch_vccnz .LBB0_106
	v_readlane_b32 s3, v254, 48
	s_bitcmp1_b32 s3, 0
	s_cbranch_scc0 .Lstag_P5a_done
	s_memrealtime s[40:41]
	s_waitcnt lgkmcnt(0)
	s_add_u32 s43, s40, 500

.Lstag_P5a_done:
	v_lshlrev_b32_e32 v4, 4, v3
	v_add_u32_e32 v1, 0x2000, v4
	v_ashrrev_i32_e32 v0, 31, v1
	v_lshrrev_b32_e32 v0, 22, v0
	v_add_u32_e32 v0, v1, v0
	v_ashrrev_i32_e32 v0, 10, v0
	v_mul_i32_i24_e32 v2, 0x400, v0
	v_sub_u32_e32 v1, v1, v2
	v_lshrrev_b32_e32 v2, 4, v1
	v_bitop3_b32 v2, v2, v1, 32 bitop3:0x6c
	v_ashrrev_i32_e32 v1, 31, v2
	v_lshrrev_b32_e32 v1, 26, v1
	v_add_u32_e32 v5, v2, v1
	v_lshlrev_b32_e32 v6, 3, v0
	v_ashrrev_i32_e32 v1, 6, v5
	v_and_b32_e32 v6, -16, v6
	v_add_u32_e32 v6, v1, v6
	v_and_b32_e32 v7, 3, v1
	s_mov_b32 s3, 0x1fffe0
	v_lshrrev_b32_e32 v8, 2, v6
	v_lshlrev_b32_e32 v9, 1, v6
	v_and_b32_e32 v5, 0xc0, v5
	v_and_or_b32 v7, v6, s3, v7
	v_and_b32_e32 v8, 4, v8
	v_and_b32_e32 v9, 24, v9
	v_sub_u32_e32 v2, v2, v5
	v_or3_b32 v7, v7, v8, v9
	v_lshlrev_b32_e32 v8, 5, v0
	v_ashrrev_i16_sdwa v2, v224, sext(v2) dst_sel:DWORD dst_unused:UNUSED_PAD src0_sel:DWORD src1_sel:BYTE_0
	v_and_b32_e32 v8, 32, v8
	v_bfe_i32 v2, v2, 0, 16
	v_add_lshl_u32 v5, v8, v2, 1
	v_lshl_add_u32 v146, v7, 11, v5
	v_lshl_add_u32 v148, v6, 11, v5
	v_bfe_i32 v5, v3, 27, 1
	v_lshrrev_b32_e32 v5, 22, v5
	v_add_u32_e32 v5, v4, v5
	v_and_b32_e32 v5, 0xfffffc00, v5
	v_sub_u32_e32 v4, v4, v5
	v_lshrrev_b32_e32 v5, 4, v4
	v_bitop3_b32 v6, v5, v4, 32 bitop3:0x6c
	v_ashrrev_i32_e32 v5, 31, v3
	v_lshrrev_b32_e32 v5, 26, v5
	v_ashrrev_i32_e32 v4, 31, v6
	v_add_u32_e32 v5, v3, v5
	v_lshrrev_b32_e32 v4, 26, v4
	v_ashrrev_i32_e32 v5, 6, v5
	v_add_u32_e32 v7, v6, v4
	v_lshlrev_b32_e32 v8, 3, v5
	v_ashrrev_i32_e32 v4, 6, v7
	v_and_b32_e32 v8, -16, v8
	v_add_u32_e32 v8, v4, v8
	v_and_b32_e32 v9, 3, v4
	v_lshrrev_b32_e32 v10, 2, v8
	v_lshlrev_b32_e32 v11, 1, v8
	v_and_b32_e32 v7, 0xc0, v7
	v_and_or_b32 v9, v8, s3, v9
	v_and_b32_e32 v10, 4, v10
	v_and_b32_e32 v11, 24, v11
	v_sub_u32_e32 v6, v6, v7
	s_ashr_i32 s17, s16, 6
	v_or3_b32 v9, v9, v10, v11
	v_lshlrev_b32_e32 v10, 5, v5
	v_ashrrev_i16_sdwa v6, v224, sext(v6) dst_sel:DWORD dst_unused:UNUSED_PAD src0_sel:DWORD src1_sel:BYTE_0
	s_lshl_b32 s2, s17, 10
	v_and_b32_e32 v10, 32, v10
	v_bfe_i32 v6, v6, 0, 16
	v_add_lshl_u32 v7, v10, v6, 1
	s_add_i32 s3, s2, 0
	v_readlane_b32 s4, v254, 12
	v_lshl_add_u32 v150, v9, 11, v7
	s_add_i32 m0, s3, 0x10000
	v_readlane_b32 s5, v254, 13
	v_readlane_b32 s12, v254, 8
	v_lshl_add_u32 v152, v8, 11, v7
	v_readlane_b32 s13, v254, 9
	s_add_i32 s11, s3, 0x6000
	s_ashr_i32 s20, s16, 8
	global_load_lds_dwordx4 v150, s[4:5]
	s_add_i32 m0, s3, 0x12000
	s_nop 0
	global_load_lds_dwordx4 v146, s[4:5]
	v_readlane_b32 s4, v254, 5
	s_add_i32 m0, s3, 0x14000
	v_readlane_b32 s5, v254, 6
	s_nop 4
	global_load_lds_dwordx4 v150, s[4:5]
	s_add_i32 m0, s3, 0x16000
	s_nop 0
	global_load_lds_dwordx4 v146, s[4:5]
	s_mov_b32 m0, s3
	s_add_i32 s4, s3, 0x2000
	global_load_lds_dwordx4 v152, s[12:13]
	s_mov_b32 m0, s4
	s_add_i32 s5, s3, 0x4000
	global_load_lds_dwordx4 v148, s[12:13]
	v_readlane_b32 s12, v254, 10
	s_mov_b32 m0, s5
	v_readlane_b32 s13, v254, 11
	s_cmp_eq_u32 s20, 1
	s_nop 3
	global_load_lds_dwordx4 v152, s[12:13]
	s_mov_b32 m0, s11
	s_nop 0
	global_load_lds_dwordx4 v148, s[12:13]
	s_cselect_b64 s[12:13], -1, 0
	s_cmp_lg_u32 s20, 1
	s_cbranch_scc1 .LBB0_75
	s_barrier

.LBB0_374:
	s_andn2_b64 vcc, exec, s[12:13]
	s_cbranch_vccnz .LBB0_396
	s_cmp_lg_u32 s5, 8
	s_cbranch_scc1 .LBB0_396
	v_readlane_b32 s2, v250, 33
	v_mov_b32_e32 v6, v222
	v_readlane_b32 s3, v250, 34
	s_andn2_b64 vcc, exec, s[2:3]
	v_readfirstlane_b32 s17, v6
	s_cbranch_vccnz .LBB0_396
	v_readlane_b32 s3, v254, 48
	s_bitcmp1_b32 s3, 0
	s_cbranch_scc0 .Lstag_P8_done
	s_memrealtime s[40:41]
	s_waitcnt lgkmcnt(0)
	s_add_u32 s43, s40, 400

.Lstag_P8_done:
	v_lshlrev_b32_e32 v3, 4, v6
	v_add_u32_e32 v1, 0x2000, v3
	v_ashrrev_i32_e32 v0, 31, v1
	v_lshrrev_b32_e32 v0, 22, v0
	v_add_u32_e32 v0, v1, v0
	v_ashrrev_i32_e32 v0, 10, v0
	v_mul_i32_i24_e32 v2, 0x400, v0
	v_sub_u32_e32 v1, v1, v2
	v_lshrrev_b32_e32 v2, 4, v1
	v_bitop3_b32 v2, v2, v1, 32 bitop3:0x6c
	v_ashrrev_i32_e32 v1, 31, v2
	v_lshrrev_b32_e32 v1, 26, v1
	v_add_u32_e32 v4, v2, v1
	v_lshlrev_b32_e32 v5, 3, v0
	v_ashrrev_i32_e32 v1, 6, v4
	v_and_b32_e32 v5, -16, v5
	v_add_u32_e32 v5, v1, v5
	v_and_b32_e32 v7, 3, v1
	s_mov_b32 s3, 0x1fffe0
	v_lshrrev_b32_e32 v8, 2, v5
	v_lshlrev_b32_e32 v9, 1, v5
	v_and_b32_e32 v4, 0xc0, v4
	v_and_or_b32 v7, v5, s3, v7
	v_and_b32_e32 v8, 4, v8
	v_and_b32_e32 v9, 24, v9
	v_sub_u32_e32 v2, v2, v4
	v_or3_b32 v7, v7, v8, v9
	v_lshlrev_b32_e32 v8, 5, v0
	v_ashrrev_i16_sdwa v2, v224, sext(v2) dst_sel:DWORD dst_unused:UNUSED_PAD src0_sel:DWORD src1_sel:BYTE_0
	v_and_b32_e32 v8, 32, v8
	v_bfe_i32 v2, v2, 0, 16
	v_add_lshl_u32 v4, v8, v2, 1
	v_lshl_add_u32 v146, v7, 11, v4
	v_lshl_add_u32 v148, v5, 11, v4
	v_bfe_i32 v4, v6, 27, 1
	v_lshrrev_b32_e32 v4, 22, v4
	v_add_u32_e32 v4, v3, v4
	v_and_b32_e32 v4, 0xfffffc00, v4
	v_sub_u32_e32 v3, v3, v4
	v_lshrrev_b32_e32 v4, 4, v3
	v_bitop3_b32 v5, v4, v3, 32 bitop3:0x6c
	v_ashrrev_i32_e32 v4, 31, v6
	v_lshrrev_b32_e32 v4, 26, v4
	v_ashrrev_i32_e32 v3, 31, v5
	v_add_u32_e32 v4, v6, v4
	v_lshrrev_b32_e32 v3, 26, v3
	v_ashrrev_i32_e32 v4, 6, v4
	v_add_u32_e32 v7, v5, v3
	v_lshlrev_b32_e32 v8, 3, v4
	v_ashrrev_i32_e32 v3, 6, v7
	v_and_b32_e32 v8, -16, v8
	v_add_u32_e32 v8, v3, v8
	v_and_b32_e32 v9, 3, v3
	v_lshrrev_b32_e32 v10, 2, v8
	v_lshlrev_b32_e32 v11, 1, v8
	v_and_b32_e32 v7, 0xc0, v7
	v_and_or_b32 v9, v8, s3, v9
	v_and_b32_e32 v10, 4, v10
	v_and_b32_e32 v11, 24, v11
	v_sub_u32_e32 v5, v5, v7
	s_ashr_i32 s15, s17, 6
	v_or3_b32 v9, v9, v10, v11
	v_lshlrev_b32_e32 v10, 5, v4
	v_ashrrev_i16_sdwa v5, v224, sext(v5) dst_sel:DWORD dst_unused:UNUSED_PAD src0_sel:DWORD src1_sel:BYTE_0
	s_lshl_b32 s2, s15, 10
	v_and_b32_e32 v10, 32, v10
	v_bfe_i32 v5, v5, 0, 16
	v_add_lshl_u32 v7, v10, v5, 1
	s_add_i32 s3, s2, 0
	v_readlane_b32 s12, v253, 15
	v_lshl_add_u32 v96, v9, 11, v7
	s_add_i32 m0, s3, 0x10000
	v_readlane_b32 s13, v253, 16
	v_lshl_add_u32 v150, v8, 11, v7
	s_add_i32 s4, s3, 0x2000
	s_add_i32 s11, s3, 0x4000
	s_add_i32 s14, s3, 0x6000
	s_ashr_i32 s16, s17, 8
	global_load_lds_dwordx4 v96, s[12:13]
	s_add_i32 m0, s3, 0x12000
	s_nop 0
	global_load_lds_dwordx4 v146, s[12:13]
	v_readlane_b32 s12, v253, 9
	s_add_i32 m0, s3, 0x14000
	v_readlane_b32 s13, v253, 10
	s_nop 4
	global_load_lds_dwordx4 v96, s[12:13]
	s_add_i32 m0, s3, 0x16000
	s_cmp_eq_u32 s16, 1
	global_load_lds_dwordx4 v146, s[12:13]
	v_readlane_b32 s12, v253, 11
	s_mov_b32 m0, s3
	v_readlane_b32 s13, v253, 12
	s_nop 4
	global_load_lds_dwordx4 v150, s[12:13]
	s_mov_b32 m0, s4
	s_nop 0
	global_load_lds_dwordx4 v148, s[12:13]
	v_readlane_b32 s12, v253, 13
	s_mov_b32 m0, s11
	v_readlane_b32 s13, v253, 14
	s_nop 4
	global_load_lds_dwordx4 v150, s[12:13]
	s_mov_b32 m0, s14
	s_nop 0
	global_load_lds_dwordx4 v148, s[12:13]
	s_cselect_b64 s[12:13], -1, 0
	s_cmp_lg_u32 s16, 1
	s_cbranch_scc1 .LBB0_379
	s_barrier

.LBB0_437:
	s_andn2_b64 vcc, exec, s[12:13]
	s_cbranch_vccnz .LBB0_454
	v_readlane_b32 s2, v250, 17
	v_mov_b32_e32 v6, v222
	v_readlane_b32 s3, v250, 18
	s_andn2_b64 vcc, exec, s[2:3]
	v_readfirstlane_b32 s17, v6
	s_cbranch_vccnz .LBB0_454
	v_readlane_b32 s3, v254, 48
	s_bitcmp1_b32 s3, 0
	s_cbranch_scc0 .Lstag_P13_done
	s_memrealtime s[40:41]
	s_waitcnt lgkmcnt(0)
	s_add_u32 s43, s40, 500

.Lstag_P13_done:
	v_lshlrev_b32_e32 v3, 4, v6
	v_add_u32_e32 v1, 0x2000, v3
	v_ashrrev_i32_e32 v0, 31, v1
	v_lshrrev_b32_e32 v0, 22, v0
	v_add_u32_e32 v0, v1, v0
	v_ashrrev_i32_e32 v0, 10, v0
	v_mul_i32_i24_e32 v2, 0x400, v0
	v_sub_u32_e32 v1, v1, v2
	v_lshrrev_b32_e32 v2, 4, v1
	v_bitop3_b32 v2, v2, v1, 32 bitop3:0x6c
	v_ashrrev_i32_e32 v1, 31, v2
	v_lshrrev_b32_e32 v1, 26, v1
	v_add_u32_e32 v4, v2, v1
	v_lshlrev_b32_e32 v5, 3, v0
	v_ashrrev_i32_e32 v1, 6, v4
	v_and_b32_e32 v5, -16, v5
	v_add_u32_e32 v5, v1, v5
	v_and_b32_e32 v7, 3, v1
	s_mov_b32 s3, 0x1fffe0
	v_lshrrev_b32_e32 v8, 2, v5
	v_lshlrev_b32_e32 v9, 1, v5
	v_and_b32_e32 v4, 0xc0, v4
	v_and_or_b32 v7, v5, s3, v7
	v_and_b32_e32 v8, 4, v8
	v_and_b32_e32 v9, 24, v9
	v_sub_u32_e32 v2, v2, v4
	v_or3_b32 v7, v7, v8, v9
	v_lshlrev_b32_e32 v8, 5, v0
	v_ashrrev_i16_sdwa v2, v224, sext(v2) dst_sel:DWORD dst_unused:UNUSED_PAD src0_sel:DWORD src1_sel:BYTE_0
	v_and_b32_e32 v8, 32, v8
	v_bfe_i32 v2, v2, 0, 16
	v_add_lshl_u32 v4, v8, v2, 1
	s_waitcnt vmcnt(0)
	v_lshl_add_u32 v130, v7, 11, v4
	v_lshl_add_u32 v132, v5, 11, v4
	v_bfe_i32 v4, v6, 27, 1
	v_lshrrev_b32_e32 v4, 22, v4
	v_add_u32_e32 v4, v3, v4
	v_and_b32_e32 v4, 0xfffffc00, v4
	v_sub_u32_e32 v3, v3, v4
	v_lshrrev_b32_e32 v4, 4, v3
	v_bitop3_b32 v5, v4, v3, 32 bitop3:0x6c
	v_ashrrev_i32_e32 v4, 31, v6
	v_lshrrev_b32_e32 v4, 26, v4
	v_ashrrev_i32_e32 v3, 31, v5
	v_add_u32_e32 v4, v6, v4
	v_lshrrev_b32_e32 v3, 26, v3
	v_ashrrev_i32_e32 v4, 6, v4
	v_add_u32_e32 v7, v5, v3
	v_lshlrev_b32_e32 v8, 3, v4
	v_ashrrev_i32_e32 v3, 6, v7
	v_and_b32_e32 v8, -16, v8
	v_add_u32_e32 v8, v3, v8
	v_and_b32_e32 v9, 3, v3
	v_lshrrev_b32_e32 v10, 2, v8
	v_lshlrev_b32_e32 v11, 1, v8
	v_and_b32_e32 v7, 0xc0, v7
	v_and_or_b32 v9, v8, s3, v9
	v_and_b32_e32 v10, 4, v10
	v_and_b32_e32 v11, 24, v11
	v_sub_u32_e32 v5, v5, v7
	s_ashr_i32 s15, s17, 6
	v_or3_b32 v9, v9, v10, v11
	v_lshlrev_b32_e32 v10, 5, v4
	v_ashrrev_i16_sdwa v5, v224, sext(v5) dst_sel:DWORD dst_unused:UNUSED_PAD src0_sel:DWORD src1_sel:BYTE_0
	s_lshl_b32 s2, s15, 10
	v_and_b32_e32 v10, 32, v10
	v_bfe_i32 v5, v5, 0, 16
	v_add_lshl_u32 v7, v10, v5, 1
	s_add_i32 s3, s2, 0
	v_readlane_b32 s12, v253, 49
	v_lshl_add_u32 v96, v9, 11, v7
	s_add_i32 m0, s3, 0x10000
	v_readlane_b32 s13, v253, 50
	v_lshl_add_u32 v134, v8, 11, v7
	s_add_i32 s4, s3, 0x2000
	s_add_i32 s11, s3, 0x4000
	s_add_i32 s14, s3, 0x6000
	s_ashr_i32 s16, s17, 8
	global_load_lds_dwordx4 v96, s[12:13]
	s_add_i32 m0, s3, 0x12000
	s_nop 0
	global_load_lds_dwordx4 v130, s[12:13]
	v_readlane_b32 s12, v253, 41
	s_add_i32 m0, s3, 0x14000
	v_readlane_b32 s13, v253, 42
	s_nop 4
	global_load_lds_dwordx4 v96, s[12:13]
	s_add_i32 m0, s3, 0x16000
	s_cmp_eq_u32 s16, 1
	global_load_lds_dwordx4 v130, s[12:13]
	v_readlane_b32 s12, v253, 45
	s_mov_b32 m0, s3
	v_readlane_b32 s13, v253, 46
	s_nop 4
	global_load_lds_dwordx4 v134, s[12:13]
	s_mov_b32 m0, s4
	s_nop 0
	global_load_lds_dwordx4 v132, s[12:13]
	v_readlane_b32 s12, v253, 47
	s_mov_b32 m0, s11
	v_readlane_b32 s13, v253, 48
	s_nop 4
	global_load_lds_dwordx4 v134, s[12:13]
	s_mov_b32 m0, s14
	s_nop 0
	global_load_lds_dwordx4 v132, s[12:13]
	s_cselect_b64 s[12:13], -1, 0
	s_cmp_lg_u32 s16, 1
	s_cbranch_scc1 .LBB0_441
	s_barrier
